# scan block regenerated: y sums via a transposing 16-step tree (17 DPP + 30 selects per 16 steps), 3-set LDS prefetch two steps ahead
# speedup vs baseline: 1.0018x; 1.0018x over previous
; #define LAS __attribute__((address_space(3)))
; __device__ __forceinline__ float row16_sum(float x) { x += dpp_mov<0xB1>(x); x += dpp_mov<0x4E>(x); x += dpp_mov<0x124>(x); x += dpp_mov<0x128>(x); return x; }
; __device__ __forceinline__ void scan_phase(const KAS Args& a, LAS unsigned char* lds, int i, const int tid_, const int bid, const int nblk) {
;     ...
;             const LAS float* buf = bufs + (c & 1) * (TC * SST); LAS float* yb = ybuf + (c & 1) * (TC * 32);
;             {
;                 const LAS float* sb = buf + 4 * cgp; const LAS float* vb = buf + 320 + rl;
;                 f32x4 kk4 = *(const LAS f32x4*)(sb), nb4 = *(const LAS f32x4*)(sb + 64), w4 = *(const LAS f32x4*)(sb + 128), k4 = *(const LAS f32x4*)(sb + 192), r4 = *(const LAS f32x4*)(sb + 256);
;                 float v = vb[0], ysel = 0.f;
; #pragma unroll
;                 for (int t = 0; t < TC; ++t) {
;                     f32x4 kk4n = kk4, nb4n = nb4, w4n = w4, k4n = k4, r4n = r4; float vn = v;
;                     if (t + 1 < TC) { const LAS float* sn = sb + (t + 1) * SST;
;                         kk4n = *(const LAS f32x4*)(sn); nb4n = *(const LAS f32x4*)(sn + 64); w4n = *(const LAS f32x4*)(sn + 128); k4n = *(const LAS f32x4*)(sn + 192); r4n = *(const LAS f32x4*)(sn + 256); vn = vb[(t + 1) * SST]; }
;                     __builtin_amdgcn_sched_barrier(0x6);
;                     float sa = fmaf(S[3], kk4[3], fmaf(S[2], kk4[2], fmaf(S[1], kk4[1], S[0] * kk4[0])));
;                     const f32x4 Tm = S * w4 + k4 * v;
;                     sa = row16_sum(sa);
;                     S = Tm + nb4 * sa;
;                     float y = fmaf(S[3], r4[3], fmaf(S[2], r4[2], fmaf(S[1], r4[1], S[0] * r4[0]))); y = row16_sum(y);
;                     ysel = (cgp == (t & 15)) ? y : ysel;
;                     if ((t & 15) == 15) yb[(t - 15 + cgp) * 32 + rl] = ysel;
;                     kk4 = kk4n; nb4 = nb4n; w4 = w4n; k4 = k4n; r4 = r4n; v = vn; }
.LBB0_190:
	s_and_b32 s2, s67, 1
	s_mul_i32 s3, s2, 0xb000
	s_add_i32 s3, s94, s3
	v_add_u32_e32 v124, s3, v114
	v_add_u32_e32 v110, s3, v120
	ds_read_b128 v[136:139], v124 offset:0
	ds_read_b128 v[140:143], v124 offset:256
	ds_read_b128 v[144:147], v124 offset:512
	ds_read_b128 v[148:151], v124 offset:768
	ds_read_b128 v[152:155], v124 offset:1024
	ds_read_b32 v156, v110 offset:1280
	ds_read_b128 v[160:163], v124 offset:1408
	ds_read_b128 v[164:167], v124 offset:1664
	ds_read_b128 v[168:171], v124 offset:1920
	ds_read_b128 v[172:175], v124 offset:2176
	ds_read_b128 v[176:179], v124 offset:2432
	ds_read_b32 v158, v110 offset:2688
	ds_read_b128 v[188:191], v124 offset:2816
	ds_read_b128 v[192:195], v124 offset:3072
	ds_read_b128 v[196:199], v124 offset:3328
	ds_read_b128 v[200:203], v124 offset:3584
	ds_read_b128 v[204:207], v124 offset:3840
	ds_read_b32 v208, v110 offset:4096
	s_lshl_b32 s2, s2, 12
	s_add_i32 s63, s64, s2
	s_add_i32 s62, s67, 1
	s_andn2_b64 vcc, exec, s[60:61]
	s_mov_b32 s8, 0xaaaaaaaa
	s_mov_b32 s9, 0xaaaaaaaa
	s_mov_b32 s10, 0xcccccccc
	s_mov_b32 s11, 0xcccccccc
	s_mov_b32 s12, 0xf0f0f0f0
	s_mov_b32 s13, 0xf0f0f0f0
	s_mov_b32 s14, 0xff00ff00
	s_mov_b32 s15, 0xff00ff00
	v_add3_u32 v122, s63, v120, v118
	s_waitcnt lgkmcnt(15)
	v_mul_f32_e32 v44, v36, v136
	v_fmac_f32_e32 v44, v37, v137
	v_fmac_f32_e32 v44, v38, v138
	v_fmac_f32_e32 v44, v39, v139
	s_waitcnt lgkmcnt(12)
	v_pk_mul_f32 v[40:41], v[148:149], v[156:157] op_sel_hi:[1,0]
	v_pk_mul_f32 v[42:43], v[150:151], v[156:157] op_sel_hi:[1,0]
	v_add_f32_dpp v2, v44, v44 quad_perm:[1,0,3,2] row_mask:0xf bank_mask:0xf bound_ctrl:1
	v_pk_fma_f32 v[40:41], v[36:37], v[144:145], v[40:41]
	v_pk_fma_f32 v[42:43], v[38:39], v[146:147], v[42:43]
	v_add_f32_dpp v2, v2, v2 quad_perm:[2,3,0,1] row_mask:0xf bank_mask:0xf bound_ctrl:1
	s_nop 1
	v_add_f32_dpp v2, v2, v2 row_ror:4 row_mask:0xf bank_mask:0xf bound_ctrl:1
	s_nop 1
	v_add_f32_dpp v2, v2, v2 row_ror:8 row_mask:0xf bank_mask:0xf bound_ctrl:1
	v_pk_fma_f32 v[36:37], v[140:141], v[2:3], v[40:41] op_sel_hi:[1,0,1]
	v_pk_fma_f32 v[38:39], v[142:143], v[2:3], v[42:43] op_sel_hi:[1,0,1]
	s_waitcnt lgkmcnt(11)
	v_mul_f32_e32 v44, v36, v160
	v_mul_f32_e32 v45, v152, v36
	v_fmac_f32_e32 v44, v37, v161
	v_fmac_f32_e32 v45, v37, v153
	v_fmac_f32_e32 v44, v38, v162
	v_fmac_f32_e32 v45, v38, v154
	v_fmac_f32_e32 v44, v39, v163
	v_fmac_f32_e32 v45, v39, v155
	s_waitcnt lgkmcnt(6)
	v_pk_mul_f32 v[40:41], v[172:173], v[158:159] op_sel_hi:[1,0]
	v_pk_mul_f32 v[42:43], v[174:175], v[158:159] op_sel_hi:[1,0]
	v_add_f32_dpp v2, v44, v44 quad_perm:[1,0,3,2] row_mask:0xf bank_mask:0xf bound_ctrl:1
	v_pk_fma_f32 v[40:41], v[36:37], v[168:169], v[40:41]
	v_pk_fma_f32 v[42:43], v[38:39], v[170:171], v[42:43]
	v_add_f32_dpp v2, v2, v2 quad_perm:[2,3,0,1] row_mask:0xf bank_mask:0xf bound_ctrl:1
	ds_read_b128 v[136:139], v124 offset:4224
	ds_read_b128 v[140:143], v124 offset:4480
	ds_read_b128 v[144:147], v124 offset:4736
	ds_read_b128 v[148:151], v124 offset:4992
	ds_read_b128 v[152:155], v124 offset:5248
	ds_read_b32 v156, v110 offset:5504
	s_nop 1
	v_add_f32_dpp v2, v2, v2 row_ror:4 row_mask:0xf bank_mask:0xf bound_ctrl:1
	s_nop 1
	v_add_f32_dpp v2, v2, v2 row_ror:8 row_mask:0xf bank_mask:0xf bound_ctrl:1
	v_pk_fma_f32 v[36:37], v[164:165], v[2:3], v[40:41] op_sel_hi:[1,0,1]
	v_pk_fma_f32 v[38:39], v[166:167], v[2:3], v[42:43] op_sel_hi:[1,0,1]
	s_waitcnt lgkmcnt(11)
	v_mul_f32_e32 v44, v36, v188
	v_mul_f32_e32 v46, v176, v36
	v_fmac_f32_e32 v44, v37, v189
	v_fmac_f32_e32 v46, v37, v177
	v_fmac_f32_e32 v44, v38, v190
	v_fmac_f32_e32 v46, v38, v178
	v_fmac_f32_e32 v44, v39, v191
	v_fmac_f32_e32 v46, v39, v179
	s_waitcnt lgkmcnt(6)
	v_pk_mul_f32 v[40:41], v[200:201], v[208:209] op_sel_hi:[1,0]
	v_pk_mul_f32 v[42:43], v[202:203], v[208:209] op_sel_hi:[1,0]
	v_add_f32_dpp v2, v44, v44 quad_perm:[1,0,3,2] row_mask:0xf bank_mask:0xf bound_ctrl:1
	v_pk_fma_f32 v[40:41], v[36:37], v[196:197], v[40:41]
	v_pk_fma_f32 v[42:43], v[38:39], v[198:199], v[42:43]
	v_add_f32_dpp v2, v2, v2 quad_perm:[2,3,0,1] row_mask:0xf bank_mask:0xf bound_ctrl:1
	v_cndmask_b32_e64 v56, v45, v46, s[8:9]
	v_cndmask_b32_e64 v57, v46, v45, s[8:9]
	s_nop 1
	v_add_f32_dpp v47, v57, v56 quad_perm:[1,0,3,2] row_mask:0xf bank_mask:0xf bound_ctrl:1
	ds_read_b128 v[160:163], v124 offset:5632
	ds_read_b128 v[164:167], v124 offset:5888
	ds_read_b128 v[168:171], v124 offset:6144
	ds_read_b128 v[172:175], v124 offset:6400
	ds_read_b128 v[176:179], v124 offset:6656
	ds_read_b32 v158, v110 offset:6912
	v_add_f32_dpp v2, v2, v2 row_ror:4 row_mask:0xf bank_mask:0xf bound_ctrl:1
	s_nop 1
	v_add_f32_dpp v2, v2, v2 row_ror:8 row_mask:0xf bank_mask:0xf bound_ctrl:1
	v_pk_fma_f32 v[36:37], v[192:193], v[2:3], v[40:41] op_sel_hi:[1,0,1]
	v_pk_fma_f32 v[38:39], v[194:195], v[2:3], v[42:43] op_sel_hi:[1,0,1]
	s_waitcnt lgkmcnt(11)
	v_mul_f32_e32 v44, v36, v136
	v_mul_f32_e32 v48, v204, v36
	v_fmac_f32_e32 v44, v37, v137
	v_fmac_f32_e32 v48, v37, v205
	v_fmac_f32_e32 v44, v38, v138
	v_fmac_f32_e32 v48, v38, v206
	v_fmac_f32_e32 v44, v39, v139
	v_fmac_f32_e32 v48, v39, v207
	s_waitcnt lgkmcnt(6)
	v_pk_mul_f32 v[40:41], v[148:149], v[156:157] op_sel_hi:[1,0]
	v_pk_mul_f32 v[42:43], v[150:151], v[156:157] op_sel_hi:[1,0]
	v_add_f32_dpp v2, v44, v44 quad_perm:[1,0,3,2] row_mask:0xf bank_mask:0xf bound_ctrl:1
	v_pk_fma_f32 v[40:41], v[36:37], v[144:145], v[40:41]
	v_pk_fma_f32 v[42:43], v[38:39], v[146:147], v[42:43]
	v_add_f32_dpp v2, v2, v2 quad_perm:[2,3,0,1] row_mask:0xf bank_mask:0xf bound_ctrl:1
	ds_read_b128 v[188:191], v124 offset:7040
	ds_read_b128 v[192:195], v124 offset:7296
	ds_read_b128 v[196:199], v124 offset:7552
	ds_read_b128 v[200:203], v124 offset:7808
	ds_read_b128 v[204:207], v124 offset:8064
	ds_read_b32 v208, v110 offset:8320
	s_nop 1
	v_add_f32_dpp v2, v2, v2 row_ror:4 row_mask:0xf bank_mask:0xf bound_ctrl:1
	s_nop 1
	v_add_f32_dpp v2, v2, v2 row_ror:8 row_mask:0xf bank_mask:0xf bound_ctrl:1
	v_pk_fma_f32 v[36:37], v[140:141], v[2:3], v[40:41] op_sel_hi:[1,0,1]
	v_pk_fma_f32 v[38:39], v[142:143], v[2:3], v[42:43] op_sel_hi:[1,0,1]
	s_waitcnt lgkmcnt(11)
; #define LAS __attribute__((address_space(3)))
; __device__ __forceinline__ float row16_sum(float x) { x += dpp_mov<0xB1>(x); x += dpp_mov<0x4E>(x); x += dpp_mov<0x124>(x); x += dpp_mov<0x128>(x); return x; }
; __device__ __forceinline__ void scan_phase(const KAS Args& a, LAS unsigned char* lds, int i, const int tid_, const int bid, const int nblk) {
;     ...
;                 for (int t = 0; t < TC; ++t) {
;                     f32x4 kk4n = kk4, nb4n = nb4, w4n = w4, k4n = k4, r4n = r4; float vn = v;
;                     if (t + 1 < TC) { const LAS float* sn = sb + (t + 1) * SST;
;                         kk4n = *(const LAS f32x4*)(sn); nb4n = *(const LAS f32x4*)(sn + 64); w4n = *(const LAS f32x4*)(sn + 128); k4n = *(const LAS f32x4*)(sn + 192); r4n = *(const LAS f32x4*)(sn + 256); vn = vb[(t + 1) * SST]; }
;                     __builtin_amdgcn_sched_barrier(0x6);
;                     float sa = fmaf(S[3], kk4[3], fmaf(S[2], kk4[2], fmaf(S[1], kk4[1], S[0] * kk4[0])));
;                     const f32x4 Tm = S * w4 + k4 * v;
;                     sa = row16_sum(sa);
;                     S = Tm + nb4 * sa;
;                     float y = fmaf(S[3], r4[3], fmaf(S[2], r4[2], fmaf(S[1], r4[1], S[0] * r4[0]))); y = row16_sum(y);
;                     ysel = (cgp == (t & 15)) ? y : ysel;
;                     if ((t & 15) == 15) yb[(t - 15 + cgp) * 32 + rl] = ysel;
;                     kk4 = kk4n; nb4 = nb4n; w4 = w4n; k4 = k4n; r4 = r4n; v = vn; }
	v_mul_f32_e32 v44, v36, v160
	v_mul_f32_e32 v49, v152, v36
	v_fmac_f32_e32 v44, v37, v161
	v_fmac_f32_e32 v49, v37, v153
	v_fmac_f32_e32 v44, v38, v162
	v_fmac_f32_e32 v49, v38, v154
	v_fmac_f32_e32 v44, v39, v163
	v_fmac_f32_e32 v49, v39, v155
	s_waitcnt lgkmcnt(6)
	v_pk_mul_f32 v[40:41], v[172:173], v[158:159] op_sel_hi:[1,0]
	v_pk_mul_f32 v[42:43], v[174:175], v[158:159] op_sel_hi:[1,0]
	v_add_f32_dpp v2, v44, v44 quad_perm:[1,0,3,2] row_mask:0xf bank_mask:0xf bound_ctrl:1
	v_pk_fma_f32 v[40:41], v[36:37], v[168:169], v[40:41]
	v_pk_fma_f32 v[42:43], v[38:39], v[170:171], v[42:43]
	v_add_f32_dpp v2, v2, v2 quad_perm:[2,3,0,1] row_mask:0xf bank_mask:0xf bound_ctrl:1
	v_cndmask_b32_e64 v56, v48, v49, s[8:9]
	v_cndmask_b32_e64 v57, v49, v48, s[8:9]
	s_nop 1
	v_add_f32_dpp v50, v57, v56 quad_perm:[1,0,3,2] row_mask:0xf bank_mask:0xf bound_ctrl:1
	v_cndmask_b32_e64 v56, v47, v50, s[10:11]
	v_cndmask_b32_e64 v57, v50, v47, s[10:11]
	s_nop 1
	v_add_f32_dpp v51, v57, v56 quad_perm:[2,3,0,1] row_mask:0xf bank_mask:0xf bound_ctrl:1
	ds_read_b128 v[136:139], v124 offset:8448
	ds_read_b128 v[140:143], v124 offset:8704
	ds_read_b128 v[144:147], v124 offset:8960
	ds_read_b128 v[148:151], v124 offset:9216
	ds_read_b128 v[152:155], v124 offset:9472
	ds_read_b32 v156, v110 offset:9728
	v_add_f32_dpp v2, v2, v2 row_ror:4 row_mask:0xf bank_mask:0xf bound_ctrl:1
	s_nop 1
	v_add_f32_dpp v2, v2, v2 row_ror:8 row_mask:0xf bank_mask:0xf bound_ctrl:1
	v_pk_fma_f32 v[36:37], v[164:165], v[2:3], v[40:41] op_sel_hi:[1,0,1]
	v_pk_fma_f32 v[38:39], v[166:167], v[2:3], v[42:43] op_sel_hi:[1,0,1]
	s_waitcnt lgkmcnt(11)
	v_mul_f32_e32 v44, v36, v188
	v_mul_f32_e32 v52, v176, v36
	v_fmac_f32_e32 v44, v37, v189
	v_fmac_f32_e32 v52, v37, v177
	v_fmac_f32_e32 v44, v38, v190
	v_fmac_f32_e32 v52, v38, v178
	v_fmac_f32_e32 v44, v39, v191
	v_fmac_f32_e32 v52, v39, v179
	s_waitcnt lgkmcnt(6)
	v_pk_mul_f32 v[40:41], v[200:201], v[208:209] op_sel_hi:[1,0]
	v_pk_mul_f32 v[42:43], v[202:203], v[208:209] op_sel_hi:[1,0]
	v_add_f32_dpp v2, v44, v44 quad_perm:[1,0,3,2] row_mask:0xf bank_mask:0xf bound_ctrl:1
	v_pk_fma_f32 v[40:41], v[36:37], v[196:197], v[40:41]
	v_pk_fma_f32 v[42:43], v[38:39], v[198:199], v[42:43]
	v_add_f32_dpp v2, v2, v2 quad_perm:[2,3,0,1] row_mask:0xf bank_mask:0xf bound_ctrl:1
	ds_read_b128 v[160:163], v124 offset:9856
	ds_read_b128 v[164:167], v124 offset:10112
	ds_read_b128 v[168:171], v124 offset:10368
	ds_read_b128 v[172:175], v124 offset:10624
	ds_read_b128 v[176:179], v124 offset:10880
	ds_read_b32 v158, v110 offset:11136
	s_nop 1
	v_add_f32_dpp v2, v2, v2 row_ror:4 row_mask:0xf bank_mask:0xf bound_ctrl:1
	s_nop 1
	v_add_f32_dpp v2, v2, v2 row_ror:8 row_mask:0xf bank_mask:0xf bound_ctrl:1
	v_pk_fma_f32 v[36:37], v[192:193], v[2:3], v[40:41] op_sel_hi:[1,0,1]
	v_pk_fma_f32 v[38:39], v[194:195], v[2:3], v[42:43] op_sel_hi:[1,0,1]
	s_waitcnt lgkmcnt(11)
	v_mul_f32_e32 v44, v36, v136
	v_mul_f32_e32 v53, v204, v36
	v_fmac_f32_e32 v44, v37, v137
	v_fmac_f32_e32 v53, v37, v205
	v_fmac_f32_e32 v44, v38, v138
	v_fmac_f32_e32 v53, v38, v206
	v_fmac_f32_e32 v44, v39, v139
	v_fmac_f32_e32 v53, v39, v207
	s_waitcnt lgkmcnt(6)
	v_pk_mul_f32 v[40:41], v[148:149], v[156:157] op_sel_hi:[1,0]
	v_pk_mul_f32 v[42:43], v[150:151], v[156:157] op_sel_hi:[1,0]
	v_add_f32_dpp v2, v44, v44 quad_perm:[1,0,3,2] row_mask:0xf bank_mask:0xf bound_ctrl:1
	v_pk_fma_f32 v[40:41], v[36:37], v[144:145], v[40:41]
	v_pk_fma_f32 v[42:43], v[38:39], v[146:147], v[42:43]
	v_add_f32_dpp v2, v2, v2 quad_perm:[2,3,0,1] row_mask:0xf bank_mask:0xf bound_ctrl:1
	v_cndmask_b32_e64 v56, v52, v53, s[8:9]
	v_cndmask_b32_e64 v57, v53, v52, s[8:9]
	s_nop 1
	v_add_f32_dpp v54, v57, v56 quad_perm:[1,0,3,2] row_mask:0xf bank_mask:0xf bound_ctrl:1
	ds_read_b128 v[188:191], v124 offset:11264
	ds_read_b128 v[192:195], v124 offset:11520
	ds_read_b128 v[196:199], v124 offset:11776
	ds_read_b128 v[200:203], v124 offset:12032
	ds_read_b128 v[204:207], v124 offset:12288
	ds_read_b32 v208, v110 offset:12544
	v_add_f32_dpp v2, v2, v2 row_ror:4 row_mask:0xf bank_mask:0xf bound_ctrl:1
	s_nop 1
	v_add_f32_dpp v2, v2, v2 row_ror:8 row_mask:0xf bank_mask:0xf bound_ctrl:1
	v_pk_fma_f32 v[36:37], v[140:141], v[2:3], v[40:41] op_sel_hi:[1,0,1]
	v_pk_fma_f32 v[38:39], v[142:143], v[2:3], v[42:43] op_sel_hi:[1,0,1]
	s_waitcnt lgkmcnt(11)
	v_mul_f32_e32 v44, v36, v160
	v_mul_f32_e32 v55, v152, v36
	v_fmac_f32_e32 v44, v37, v161
	v_fmac_f32_e32 v55, v37, v153
	v_fmac_f32_e32 v44, v38, v162
	v_fmac_f32_e32 v55, v38, v154
	v_fmac_f32_e32 v44, v39, v163
	v_fmac_f32_e32 v55, v39, v155
	s_waitcnt lgkmcnt(6)
	v_pk_mul_f32 v[40:41], v[172:173], v[158:159] op_sel_hi:[1,0]
	v_pk_mul_f32 v[42:43], v[174:175], v[158:159] op_sel_hi:[1,0]
	v_add_f32_dpp v2, v44, v44 quad_perm:[1,0,3,2] row_mask:0xf bank_mask:0xf bound_ctrl:1
	v_pk_fma_f32 v[40:41], v[36:37], v[168:169], v[40:41]
	v_pk_fma_f32 v[42:43], v[38:39], v[170:171], v[42:43]
	v_add_f32_dpp v2, v2, v2 quad_perm:[2,3,0,1] row_mask:0xf bank_mask:0xf bound_ctrl:1
	ds_read_b128 v[136:139], v124 offset:12672
	ds_read_b128 v[140:143], v124 offset:12928
	ds_read_b128 v[144:147], v124 offset:13184
	ds_read_b128 v[148:151], v124 offset:13440
	ds_read_b128 v[152:155], v124 offset:13696
	ds_read_b32 v156, v110 offset:13952
	s_nop 1
	v_add_f32_dpp v2, v2, v2 row_ror:4 row_mask:0xf bank_mask:0xf bound_ctrl:1
	s_nop 1
	v_add_f32_dpp v2, v2, v2 row_ror:8 row_mask:0xf bank_mask:0xf bound_ctrl:1
	v_pk_fma_f32 v[36:37], v[164:165], v[2:3], v[40:41] op_sel_hi:[1,0,1]
	v_pk_fma_f32 v[38:39], v[166:167], v[2:3], v[42:43] op_sel_hi:[1,0,1]
	s_waitcnt lgkmcnt(11)
; #define LAS __attribute__((address_space(3)))
; __device__ __forceinline__ float row16_sum(float x) { x += dpp_mov<0xB1>(x); x += dpp_mov<0x4E>(x); x += dpp_mov<0x124>(x); x += dpp_mov<0x128>(x); return x; }
; __device__ __forceinline__ void scan_phase(const KAS Args& a, LAS unsigned char* lds, int i, const int tid_, const int bid, const int nblk) {
;     ...
;                 for (int t = 0; t < TC; ++t) {
;                     f32x4 kk4n = kk4, nb4n = nb4, w4n = w4, k4n = k4, r4n = r4; float vn = v;
;                     if (t + 1 < TC) { const LAS float* sn = sb + (t + 1) * SST;
;                         kk4n = *(const LAS f32x4*)(sn); nb4n = *(const LAS f32x4*)(sn + 64); w4n = *(const LAS f32x4*)(sn + 128); k4n = *(const LAS f32x4*)(sn + 192); r4n = *(const LAS f32x4*)(sn + 256); vn = vb[(t + 1) * SST]; }
;                     __builtin_amdgcn_sched_barrier(0x6);
;                     float sa = fmaf(S[3], kk4[3], fmaf(S[2], kk4[2], fmaf(S[1], kk4[1], S[0] * kk4[0])));
;                     const f32x4 Tm = S * w4 + k4 * v;
;                     sa = row16_sum(sa);
;                     S = Tm + nb4 * sa;
;                     float y = fmaf(S[3], r4[3], fmaf(S[2], r4[2], fmaf(S[1], r4[1], S[0] * r4[0]))); y = row16_sum(y);
;                     ysel = (cgp == (t & 15)) ? y : ysel;
;                     if ((t & 15) == 15) yb[(t - 15 + cgp) * 32 + rl] = ysel;
;                     kk4 = kk4n; nb4 = nb4n; w4 = w4n; k4 = k4n; r4 = r4n; v = vn; }
	v_mul_f32_e32 v44, v36, v188
	v_mul_f32_e32 v58, v176, v36
	v_fmac_f32_e32 v44, v37, v189
	v_fmac_f32_e32 v58, v37, v177
	v_fmac_f32_e32 v44, v38, v190
	v_fmac_f32_e32 v58, v38, v178
	v_fmac_f32_e32 v44, v39, v191
	v_fmac_f32_e32 v58, v39, v179
	s_waitcnt lgkmcnt(6)
	v_pk_mul_f32 v[40:41], v[200:201], v[208:209] op_sel_hi:[1,0]
	v_pk_mul_f32 v[42:43], v[202:203], v[208:209] op_sel_hi:[1,0]
	v_add_f32_dpp v2, v44, v44 quad_perm:[1,0,3,2] row_mask:0xf bank_mask:0xf bound_ctrl:1
	v_pk_fma_f32 v[40:41], v[36:37], v[196:197], v[40:41]
	v_pk_fma_f32 v[42:43], v[38:39], v[198:199], v[42:43]
	v_add_f32_dpp v2, v2, v2 quad_perm:[2,3,0,1] row_mask:0xf bank_mask:0xf bound_ctrl:1
	v_cndmask_b32_e64 v56, v55, v58, s[8:9]
	v_cndmask_b32_e64 v57, v58, v55, s[8:9]
	s_nop 1
	v_add_f32_dpp v59, v57, v56 quad_perm:[1,0,3,2] row_mask:0xf bank_mask:0xf bound_ctrl:1
	v_cndmask_b32_e64 v56, v54, v59, s[10:11]
	v_cndmask_b32_e64 v57, v59, v54, s[10:11]
	s_nop 1
	v_add_f32_dpp v60, v57, v56 quad_perm:[2,3,0,1] row_mask:0xf bank_mask:0xf bound_ctrl:1
	v_cndmask_b32_e64 v56, v51, v60, s[12:13]
	v_cndmask_b32_e64 v57, v60, v51, s[12:13]
	s_nop 1
	v_add_f32_dpp v61, v57, v56 row_shl:4 row_mask:0xf bank_mask:0x5
	s_nop 1
	v_add_f32_dpp v61, v57, v56 row_shr:4 row_mask:0xf bank_mask:0xa
	ds_read_b128 v[160:163], v124 offset:14080
	ds_read_b128 v[164:167], v124 offset:14336
	ds_read_b128 v[168:171], v124 offset:14592
	ds_read_b128 v[172:175], v124 offset:14848
	ds_read_b128 v[176:179], v124 offset:15104
	ds_read_b32 v158, v110 offset:15360
	v_add_f32_dpp v2, v2, v2 row_ror:4 row_mask:0xf bank_mask:0xf bound_ctrl:1
	s_nop 1
	v_add_f32_dpp v2, v2, v2 row_ror:8 row_mask:0xf bank_mask:0xf bound_ctrl:1
	v_pk_fma_f32 v[36:37], v[192:193], v[2:3], v[40:41] op_sel_hi:[1,0,1]
	v_pk_fma_f32 v[38:39], v[194:195], v[2:3], v[42:43] op_sel_hi:[1,0,1]
	s_waitcnt lgkmcnt(11)
	v_mul_f32_e32 v44, v36, v136
	v_mul_f32_e32 v62, v204, v36
	v_fmac_f32_e32 v44, v37, v137
	v_fmac_f32_e32 v62, v37, v205
	v_fmac_f32_e32 v44, v38, v138
	v_fmac_f32_e32 v62, v38, v206
	v_fmac_f32_e32 v44, v39, v139
	v_fmac_f32_e32 v62, v39, v207
	s_waitcnt lgkmcnt(6)
	v_pk_mul_f32 v[40:41], v[148:149], v[156:157] op_sel_hi:[1,0]
	v_pk_mul_f32 v[42:43], v[150:151], v[156:157] op_sel_hi:[1,0]
	v_add_f32_dpp v2, v44, v44 quad_perm:[1,0,3,2] row_mask:0xf bank_mask:0xf bound_ctrl:1
	v_pk_fma_f32 v[40:41], v[36:37], v[144:145], v[40:41]
	v_pk_fma_f32 v[42:43], v[38:39], v[146:147], v[42:43]
	v_add_f32_dpp v2, v2, v2 quad_perm:[2,3,0,1] row_mask:0xf bank_mask:0xf bound_ctrl:1
	ds_read_b128 v[188:191], v124 offset:15488
	ds_read_b128 v[192:195], v124 offset:15744
	ds_read_b128 v[196:199], v124 offset:16000
	ds_read_b128 v[200:203], v124 offset:16256
	ds_read_b128 v[204:207], v124 offset:16512
	ds_read_b32 v208, v110 offset:16768
	s_nop 1
	v_add_f32_dpp v2, v2, v2 row_ror:4 row_mask:0xf bank_mask:0xf bound_ctrl:1
	s_nop 1
	v_add_f32_dpp v2, v2, v2 row_ror:8 row_mask:0xf bank_mask:0xf bound_ctrl:1
	v_pk_fma_f32 v[36:37], v[140:141], v[2:3], v[40:41] op_sel_hi:[1,0,1]
	v_pk_fma_f32 v[38:39], v[142:143], v[2:3], v[42:43] op_sel_hi:[1,0,1]
	s_waitcnt lgkmcnt(11)
	v_mul_f32_e32 v44, v36, v160
	v_mul_f32_e32 v63, v152, v36
	v_fmac_f32_e32 v44, v37, v161
	v_fmac_f32_e32 v63, v37, v153
	v_fmac_f32_e32 v44, v38, v162
	v_fmac_f32_e32 v63, v38, v154
	v_fmac_f32_e32 v44, v39, v163
	v_fmac_f32_e32 v63, v39, v155
	s_waitcnt lgkmcnt(6)
	v_pk_mul_f32 v[40:41], v[172:173], v[158:159] op_sel_hi:[1,0]
	v_pk_mul_f32 v[42:43], v[174:175], v[158:159] op_sel_hi:[1,0]
	v_add_f32_dpp v2, v44, v44 quad_perm:[1,0,3,2] row_mask:0xf bank_mask:0xf bound_ctrl:1
	v_pk_fma_f32 v[40:41], v[36:37], v[168:169], v[40:41]
	v_pk_fma_f32 v[42:43], v[38:39], v[170:171], v[42:43]
	v_add_f32_dpp v2, v2, v2 quad_perm:[2,3,0,1] row_mask:0xf bank_mask:0xf bound_ctrl:1
	v_cndmask_b32_e64 v56, v62, v63, s[8:9]
	v_cndmask_b32_e64 v57, v63, v62, s[8:9]
	s_nop 1
	v_add_f32_dpp v64, v57, v56 quad_perm:[1,0,3,2] row_mask:0xf bank_mask:0xf bound_ctrl:1
	ds_read_b128 v[136:139], v124 offset:16896
	ds_read_b128 v[140:143], v124 offset:17152
	ds_read_b128 v[144:147], v124 offset:17408
	ds_read_b128 v[148:151], v124 offset:17664
	ds_read_b128 v[152:155], v124 offset:17920
	ds_read_b32 v156, v110 offset:18176
	v_add_f32_dpp v2, v2, v2 row_ror:4 row_mask:0xf bank_mask:0xf bound_ctrl:1
	s_nop 1
	v_add_f32_dpp v2, v2, v2 row_ror:8 row_mask:0xf bank_mask:0xf bound_ctrl:1
	v_pk_fma_f32 v[36:37], v[164:165], v[2:3], v[40:41] op_sel_hi:[1,0,1]
	v_pk_fma_f32 v[38:39], v[166:167], v[2:3], v[42:43] op_sel_hi:[1,0,1]
	s_waitcnt lgkmcnt(11)
	v_mul_f32_e32 v44, v36, v188
	v_mul_f32_e32 v65, v176, v36
	v_fmac_f32_e32 v44, v37, v189
	v_fmac_f32_e32 v65, v37, v177
	v_fmac_f32_e32 v44, v38, v190
	v_fmac_f32_e32 v65, v38, v178
	v_fmac_f32_e32 v44, v39, v191
	v_fmac_f32_e32 v65, v39, v179
	s_waitcnt lgkmcnt(6)
	v_pk_mul_f32 v[40:41], v[200:201], v[208:209] op_sel_hi:[1,0]
	v_pk_mul_f32 v[42:43], v[202:203], v[208:209] op_sel_hi:[1,0]
	v_add_f32_dpp v2, v44, v44 quad_perm:[1,0,3,2] row_mask:0xf bank_mask:0xf bound_ctrl:1
	v_pk_fma_f32 v[40:41], v[36:37], v[196:197], v[40:41]
	v_pk_fma_f32 v[42:43], v[38:39], v[198:199], v[42:43]
	v_add_f32_dpp v2, v2, v2 quad_perm:[2,3,0,1] row_mask:0xf bank_mask:0xf bound_ctrl:1
	ds_read_b128 v[160:163], v124 offset:18304
	ds_read_b128 v[164:167], v124 offset:18560
	ds_read_b128 v[168:171], v124 offset:18816
	ds_read_b128 v[172:175], v124 offset:19072
	ds_read_b128 v[176:179], v124 offset:19328
	ds_read_b32 v158, v110 offset:19584
	s_nop 1
	v_add_f32_dpp v2, v2, v2 row_ror:4 row_mask:0xf bank_mask:0xf bound_ctrl:1
	s_nop 1
	v_add_f32_dpp v2, v2, v2 row_ror:8 row_mask:0xf bank_mask:0xf bound_ctrl:1
	v_pk_fma_f32 v[36:37], v[192:193], v[2:3], v[40:41] op_sel_hi:[1,0,1]
	v_pk_fma_f32 v[38:39], v[194:195], v[2:3], v[42:43] op_sel_hi:[1,0,1]
	s_waitcnt lgkmcnt(11)
; #define LAS __attribute__((address_space(3)))
; __device__ __forceinline__ float row16_sum(float x) { x += dpp_mov<0xB1>(x); x += dpp_mov<0x4E>(x); x += dpp_mov<0x124>(x); x += dpp_mov<0x128>(x); return x; }
; __device__ __forceinline__ void scan_phase(const KAS Args& a, LAS unsigned char* lds, int i, const int tid_, const int bid, const int nblk) {
;     ...
;                 for (int t = 0; t < TC; ++t) {
;                     f32x4 kk4n = kk4, nb4n = nb4, w4n = w4, k4n = k4, r4n = r4; float vn = v;
;                     if (t + 1 < TC) { const LAS float* sn = sb + (t + 1) * SST;
;                         kk4n = *(const LAS f32x4*)(sn); nb4n = *(const LAS f32x4*)(sn + 64); w4n = *(const LAS f32x4*)(sn + 128); k4n = *(const LAS f32x4*)(sn + 192); r4n = *(const LAS f32x4*)(sn + 256); vn = vb[(t + 1) * SST]; }
;                     __builtin_amdgcn_sched_barrier(0x6);
;                     float sa = fmaf(S[3], kk4[3], fmaf(S[2], kk4[2], fmaf(S[1], kk4[1], S[0] * kk4[0])));
;                     const f32x4 Tm = S * w4 + k4 * v;
;                     sa = row16_sum(sa);
;                     S = Tm + nb4 * sa;
;                     float y = fmaf(S[3], r4[3], fmaf(S[2], r4[2], fmaf(S[1], r4[1], S[0] * r4[0]))); y = row16_sum(y);
;                     ysel = (cgp == (t & 15)) ? y : ysel;
;                     if ((t & 15) == 15) yb[(t - 15 + cgp) * 32 + rl] = ysel;
;                     kk4 = kk4n; nb4 = nb4n; w4 = w4n; k4 = k4n; r4 = r4n; v = vn; }
	v_mul_f32_e32 v44, v36, v136
	v_mul_f32_e32 v66, v204, v36
	v_fmac_f32_e32 v44, v37, v137
	v_fmac_f32_e32 v66, v37, v205
	v_fmac_f32_e32 v44, v38, v138
	v_fmac_f32_e32 v66, v38, v206
	v_fmac_f32_e32 v44, v39, v139
	v_fmac_f32_e32 v66, v39, v207
	s_waitcnt lgkmcnt(6)
	v_pk_mul_f32 v[40:41], v[148:149], v[156:157] op_sel_hi:[1,0]
	v_pk_mul_f32 v[42:43], v[150:151], v[156:157] op_sel_hi:[1,0]
	v_add_f32_dpp v2, v44, v44 quad_perm:[1,0,3,2] row_mask:0xf bank_mask:0xf bound_ctrl:1
	v_pk_fma_f32 v[40:41], v[36:37], v[144:145], v[40:41]
	v_pk_fma_f32 v[42:43], v[38:39], v[146:147], v[42:43]
	v_add_f32_dpp v2, v2, v2 quad_perm:[2,3,0,1] row_mask:0xf bank_mask:0xf bound_ctrl:1
	v_cndmask_b32_e64 v56, v65, v66, s[8:9]
	v_cndmask_b32_e64 v57, v66, v65, s[8:9]
	s_nop 1
	v_add_f32_dpp v67, v57, v56 quad_perm:[1,0,3,2] row_mask:0xf bank_mask:0xf bound_ctrl:1
	v_cndmask_b32_e64 v56, v64, v67, s[10:11]
	v_cndmask_b32_e64 v57, v67, v64, s[10:11]
	s_nop 1
	v_add_f32_dpp v45, v57, v56 quad_perm:[2,3,0,1] row_mask:0xf bank_mask:0xf bound_ctrl:1
	ds_read_b128 v[188:191], v124 offset:19712
	ds_read_b128 v[192:195], v124 offset:19968
	ds_read_b128 v[196:199], v124 offset:20224
	ds_read_b128 v[200:203], v124 offset:20480
	ds_read_b128 v[204:207], v124 offset:20736
	ds_read_b32 v208, v110 offset:20992
	v_add_f32_dpp v2, v2, v2 row_ror:4 row_mask:0xf bank_mask:0xf bound_ctrl:1
	s_nop 1
	v_add_f32_dpp v2, v2, v2 row_ror:8 row_mask:0xf bank_mask:0xf bound_ctrl:1
	v_pk_fma_f32 v[36:37], v[140:141], v[2:3], v[40:41] op_sel_hi:[1,0,1]
	v_pk_fma_f32 v[38:39], v[142:143], v[2:3], v[42:43] op_sel_hi:[1,0,1]
	s_waitcnt lgkmcnt(11)
	v_mul_f32_e32 v44, v36, v160
	v_mul_f32_e32 v46, v152, v36
	v_fmac_f32_e32 v44, v37, v161
	v_fmac_f32_e32 v46, v37, v153
	v_fmac_f32_e32 v44, v38, v162
	v_fmac_f32_e32 v46, v38, v154
	v_fmac_f32_e32 v44, v39, v163
	v_fmac_f32_e32 v46, v39, v155
	s_waitcnt lgkmcnt(6)
	v_pk_mul_f32 v[40:41], v[172:173], v[158:159] op_sel_hi:[1,0]
	v_pk_mul_f32 v[42:43], v[174:175], v[158:159] op_sel_hi:[1,0]
	v_add_f32_dpp v2, v44, v44 quad_perm:[1,0,3,2] row_mask:0xf bank_mask:0xf bound_ctrl:1
	v_pk_fma_f32 v[40:41], v[36:37], v[168:169], v[40:41]
	v_pk_fma_f32 v[42:43], v[38:39], v[170:171], v[42:43]
	v_add_f32_dpp v2, v2, v2 quad_perm:[2,3,0,1] row_mask:0xf bank_mask:0xf bound_ctrl:1
	ds_read_b128 v[136:139], v124 offset:21120
	ds_read_b128 v[140:143], v124 offset:21376
	ds_read_b128 v[144:147], v124 offset:21632
	ds_read_b128 v[148:151], v124 offset:21888
	ds_read_b128 v[152:155], v124 offset:22144
	ds_read_b32 v156, v110 offset:22400
	s_nop 1
	v_add_f32_dpp v2, v2, v2 row_ror:4 row_mask:0xf bank_mask:0xf bound_ctrl:1
	s_nop 1
	v_add_f32_dpp v2, v2, v2 row_ror:8 row_mask:0xf bank_mask:0xf bound_ctrl:1
	v_pk_fma_f32 v[36:37], v[164:165], v[2:3], v[40:41] op_sel_hi:[1,0,1]
	v_pk_fma_f32 v[38:39], v[166:167], v[2:3], v[42:43] op_sel_hi:[1,0,1]
	s_waitcnt lgkmcnt(11)
	v_mul_f32_e32 v44, v36, v188
	v_mul_f32_e32 v48, v176, v36
	v_fmac_f32_e32 v44, v37, v189
	v_fmac_f32_e32 v48, v37, v177
	v_fmac_f32_e32 v44, v38, v190
	v_fmac_f32_e32 v48, v38, v178
	v_fmac_f32_e32 v44, v39, v191
	v_fmac_f32_e32 v48, v39, v179
	s_waitcnt lgkmcnt(6)
	v_pk_mul_f32 v[40:41], v[200:201], v[208:209] op_sel_hi:[1,0]
	v_pk_mul_f32 v[42:43], v[202:203], v[208:209] op_sel_hi:[1,0]
	v_add_f32_dpp v2, v44, v44 quad_perm:[1,0,3,2] row_mask:0xf bank_mask:0xf bound_ctrl:1
	v_pk_fma_f32 v[40:41], v[36:37], v[196:197], v[40:41]
	v_pk_fma_f32 v[42:43], v[38:39], v[198:199], v[42:43]
	v_add_f32_dpp v2, v2, v2 quad_perm:[2,3,0,1] row_mask:0xf bank_mask:0xf bound_ctrl:1
	v_cndmask_b32_e64 v56, v46, v48, s[8:9]
	v_cndmask_b32_e64 v57, v48, v46, s[8:9]
	s_nop 1
	v_add_f32_dpp v49, v57, v56 quad_perm:[1,0,3,2] row_mask:0xf bank_mask:0xf bound_ctrl:1
	ds_read_b128 v[160:163], v124 offset:22528
	ds_read_b128 v[164:167], v124 offset:22784
	ds_read_b128 v[168:171], v124 offset:23040
	ds_read_b128 v[172:175], v124 offset:23296
	ds_read_b128 v[176:179], v124 offset:23552
	ds_read_b32 v158, v110 offset:23808
	v_add_f32_dpp v2, v2, v2 row_ror:4 row_mask:0xf bank_mask:0xf bound_ctrl:1
	s_nop 1
	v_add_f32_dpp v2, v2, v2 row_ror:8 row_mask:0xf bank_mask:0xf bound_ctrl:1
	v_pk_fma_f32 v[36:37], v[192:193], v[2:3], v[40:41] op_sel_hi:[1,0,1]
	v_pk_fma_f32 v[38:39], v[194:195], v[2:3], v[42:43] op_sel_hi:[1,0,1]
	s_waitcnt lgkmcnt(11)
	v_mul_f32_e32 v44, v36, v136
	v_mul_f32_e32 v47, v204, v36
	v_fmac_f32_e32 v44, v37, v137
	v_fmac_f32_e32 v47, v37, v205
	v_fmac_f32_e32 v44, v38, v138
	v_fmac_f32_e32 v47, v38, v206
	v_fmac_f32_e32 v44, v39, v139
	v_fmac_f32_e32 v47, v39, v207
	s_waitcnt lgkmcnt(6)
	v_pk_mul_f32 v[40:41], v[148:149], v[156:157] op_sel_hi:[1,0]
	v_pk_mul_f32 v[42:43], v[150:151], v[156:157] op_sel_hi:[1,0]
	v_add_f32_dpp v2, v44, v44 quad_perm:[1,0,3,2] row_mask:0xf bank_mask:0xf bound_ctrl:1
	v_pk_fma_f32 v[40:41], v[36:37], v[144:145], v[40:41]
	v_pk_fma_f32 v[42:43], v[38:39], v[146:147], v[42:43]
	v_add_f32_dpp v2, v2, v2 quad_perm:[2,3,0,1] row_mask:0xf bank_mask:0xf bound_ctrl:1
	ds_read_b128 v[188:191], v124 offset:23936
	ds_read_b128 v[192:195], v124 offset:24192
	ds_read_b128 v[196:199], v124 offset:24448
	ds_read_b128 v[200:203], v124 offset:24704
	ds_read_b128 v[204:207], v124 offset:24960
	ds_read_b32 v208, v110 offset:25216
	s_nop 1
	v_add_f32_dpp v2, v2, v2 row_ror:4 row_mask:0xf bank_mask:0xf bound_ctrl:1
	s_nop 1
	v_add_f32_dpp v2, v2, v2 row_ror:8 row_mask:0xf bank_mask:0xf bound_ctrl:1
	v_pk_fma_f32 v[36:37], v[140:141], v[2:3], v[40:41] op_sel_hi:[1,0,1]
	v_pk_fma_f32 v[38:39], v[142:143], v[2:3], v[42:43] op_sel_hi:[1,0,1]
	s_waitcnt lgkmcnt(11)
; #define LAS __attribute__((address_space(3)))
; __device__ __forceinline__ float row16_sum(float x) { x += dpp_mov<0xB1>(x); x += dpp_mov<0x4E>(x); x += dpp_mov<0x124>(x); x += dpp_mov<0x128>(x); return x; }
; __device__ __forceinline__ void scan_phase(const KAS Args& a, LAS unsigned char* lds, int i, const int tid_, const int bid, const int nblk) {
;     ...
;                 for (int t = 0; t < TC; ++t) {
;                     f32x4 kk4n = kk4, nb4n = nb4, w4n = w4, k4n = k4, r4n = r4; float vn = v;
;                     if (t + 1 < TC) { const LAS float* sn = sb + (t + 1) * SST;
;                         kk4n = *(const LAS f32x4*)(sn); nb4n = *(const LAS f32x4*)(sn + 64); w4n = *(const LAS f32x4*)(sn + 128); k4n = *(const LAS f32x4*)(sn + 192); r4n = *(const LAS f32x4*)(sn + 256); vn = vb[(t + 1) * SST]; }
;                     __builtin_amdgcn_sched_barrier(0x6);
;                     float sa = fmaf(S[3], kk4[3], fmaf(S[2], kk4[2], fmaf(S[1], kk4[1], S[0] * kk4[0])));
;                     const f32x4 Tm = S * w4 + k4 * v;
;                     sa = row16_sum(sa);
;                     S = Tm + nb4 * sa;
;                     float y = fmaf(S[3], r4[3], fmaf(S[2], r4[2], fmaf(S[1], r4[1], S[0] * r4[0]))); y = row16_sum(y);
;                     ysel = (cgp == (t & 15)) ? y : ysel;
;                     if ((t & 15) == 15) yb[(t - 15 + cgp) * 32 + rl] = ysel;
;                     kk4 = kk4n; nb4 = nb4n; w4 = w4n; k4 = k4n; r4 = r4n; v = vn; }
	v_mul_f32_e32 v44, v36, v160
	v_mul_f32_e32 v50, v152, v36
	v_fmac_f32_e32 v44, v37, v161
	v_fmac_f32_e32 v50, v37, v153
	v_fmac_f32_e32 v44, v38, v162
	v_fmac_f32_e32 v50, v38, v154
	v_fmac_f32_e32 v44, v39, v163
	v_fmac_f32_e32 v50, v39, v155
	s_waitcnt lgkmcnt(6)
	v_pk_mul_f32 v[40:41], v[172:173], v[158:159] op_sel_hi:[1,0]
	v_pk_mul_f32 v[42:43], v[174:175], v[158:159] op_sel_hi:[1,0]
	v_add_f32_dpp v2, v44, v44 quad_perm:[1,0,3,2] row_mask:0xf bank_mask:0xf bound_ctrl:1
	v_pk_fma_f32 v[40:41], v[36:37], v[168:169], v[40:41]
	v_pk_fma_f32 v[42:43], v[38:39], v[170:171], v[42:43]
	v_add_f32_dpp v2, v2, v2 quad_perm:[2,3,0,1] row_mask:0xf bank_mask:0xf bound_ctrl:1
	v_cndmask_b32_e64 v56, v47, v50, s[8:9]
	v_cndmask_b32_e64 v57, v50, v47, s[8:9]
	s_nop 1
	v_add_f32_dpp v52, v57, v56 quad_perm:[1,0,3,2] row_mask:0xf bank_mask:0xf bound_ctrl:1
	v_cndmask_b32_e64 v56, v49, v52, s[10:11]
	v_cndmask_b32_e64 v57, v52, v49, s[10:11]
	s_nop 1
	v_add_f32_dpp v53, v57, v56 quad_perm:[2,3,0,1] row_mask:0xf bank_mask:0xf bound_ctrl:1
	v_cndmask_b32_e64 v56, v45, v53, s[12:13]
	v_cndmask_b32_e64 v57, v53, v45, s[12:13]
	s_nop 1
	v_add_f32_dpp v55, v57, v56 row_shl:4 row_mask:0xf bank_mask:0x5
	s_nop 1
	v_add_f32_dpp v55, v57, v56 row_shr:4 row_mask:0xf bank_mask:0xa
	v_cndmask_b32_e64 v56, v61, v55, s[14:15]
	v_cndmask_b32_e64 v57, v55, v61, s[14:15]
	s_nop 1
	v_add_f32_dpp v58, v57, v56 row_ror:8 row_mask:0xf bank_mask:0xf bound_ctrl:1
	ds_read_b128 v[136:139], v124 offset:25344
	ds_read_b128 v[140:143], v124 offset:25600
	ds_read_b128 v[144:147], v124 offset:25856
	ds_read_b128 v[148:151], v124 offset:26112
	ds_read_b128 v[152:155], v124 offset:26368
	ds_read_b32 v156, v110 offset:26624
	v_add_f32_dpp v2, v2, v2 row_ror:4 row_mask:0xf bank_mask:0xf bound_ctrl:1
	s_nop 1
	v_add_f32_dpp v2, v2, v2 row_ror:8 row_mask:0xf bank_mask:0xf bound_ctrl:1
	ds_write_b32 v122, v58
	v_pk_fma_f32 v[36:37], v[164:165], v[2:3], v[40:41] op_sel_hi:[1,0,1]
	v_pk_fma_f32 v[38:39], v[166:167], v[2:3], v[42:43] op_sel_hi:[1,0,1]
	s_waitcnt lgkmcnt(12)
	v_mul_f32_e32 v44, v36, v188
	v_mul_f32_e32 v54, v176, v36
	v_fmac_f32_e32 v44, v37, v189
	v_fmac_f32_e32 v54, v37, v177
	v_fmac_f32_e32 v44, v38, v190
	v_fmac_f32_e32 v54, v38, v178
	v_fmac_f32_e32 v44, v39, v191
	v_fmac_f32_e32 v54, v39, v179
	s_waitcnt lgkmcnt(7)
	v_pk_mul_f32 v[40:41], v[200:201], v[208:209] op_sel_hi:[1,0]
	v_pk_mul_f32 v[42:43], v[202:203], v[208:209] op_sel_hi:[1,0]
	v_add_f32_dpp v2, v44, v44 quad_perm:[1,0,3,2] row_mask:0xf bank_mask:0xf bound_ctrl:1
	v_pk_fma_f32 v[40:41], v[36:37], v[196:197], v[40:41]
	v_pk_fma_f32 v[42:43], v[38:39], v[198:199], v[42:43]
	v_add_f32_dpp v2, v2, v2 quad_perm:[2,3,0,1] row_mask:0xf bank_mask:0xf bound_ctrl:1
	ds_read_b128 v[160:163], v124 offset:26752
	ds_read_b128 v[164:167], v124 offset:27008
	ds_read_b128 v[168:171], v124 offset:27264
	ds_read_b128 v[172:175], v124 offset:27520
	ds_read_b128 v[176:179], v124 offset:27776
	ds_read_b32 v158, v110 offset:28032
	s_nop 1
	v_add_f32_dpp v2, v2, v2 row_ror:4 row_mask:0xf bank_mask:0xf bound_ctrl:1
	s_nop 1
	v_add_f32_dpp v2, v2, v2 row_ror:8 row_mask:0xf bank_mask:0xf bound_ctrl:1
	v_pk_fma_f32 v[36:37], v[192:193], v[2:3], v[40:41] op_sel_hi:[1,0,1]
	v_pk_fma_f32 v[38:39], v[194:195], v[2:3], v[42:43] op_sel_hi:[1,0,1]
	s_waitcnt lgkmcnt(12)
	v_mul_f32_e32 v44, v36, v136
	v_mul_f32_e32 v59, v204, v36
	v_fmac_f32_e32 v44, v37, v137
	v_fmac_f32_e32 v59, v37, v205
	v_fmac_f32_e32 v44, v38, v138
	v_fmac_f32_e32 v59, v38, v206
	v_fmac_f32_e32 v44, v39, v139
	v_fmac_f32_e32 v59, v39, v207
	s_waitcnt lgkmcnt(7)
	v_pk_mul_f32 v[40:41], v[148:149], v[156:157] op_sel_hi:[1,0]
	v_pk_mul_f32 v[42:43], v[150:151], v[156:157] op_sel_hi:[1,0]
	v_add_f32_dpp v2, v44, v44 quad_perm:[1,0,3,2] row_mask:0xf bank_mask:0xf bound_ctrl:1
	v_pk_fma_f32 v[40:41], v[36:37], v[144:145], v[40:41]
	v_pk_fma_f32 v[42:43], v[38:39], v[146:147], v[42:43]
	v_add_f32_dpp v2, v2, v2 quad_perm:[2,3,0,1] row_mask:0xf bank_mask:0xf bound_ctrl:1
	v_cndmask_b32_e64 v56, v54, v59, s[8:9]
	v_cndmask_b32_e64 v57, v59, v54, s[8:9]
	s_nop 1
	v_add_f32_dpp v51, v57, v56 quad_perm:[1,0,3,2] row_mask:0xf bank_mask:0xf bound_ctrl:1
	ds_read_b128 v[188:191], v124 offset:28160
	ds_read_b128 v[192:195], v124 offset:28416
	ds_read_b128 v[196:199], v124 offset:28672
	ds_read_b128 v[200:203], v124 offset:28928
	ds_read_b128 v[204:207], v124 offset:29184
	ds_read_b32 v208, v110 offset:29440
	v_add_f32_dpp v2, v2, v2 row_ror:4 row_mask:0xf bank_mask:0xf bound_ctrl:1
	s_nop 1
	v_add_f32_dpp v2, v2, v2 row_ror:8 row_mask:0xf bank_mask:0xf bound_ctrl:1
	v_pk_fma_f32 v[36:37], v[140:141], v[2:3], v[40:41] op_sel_hi:[1,0,1]
	v_pk_fma_f32 v[38:39], v[142:143], v[2:3], v[42:43] op_sel_hi:[1,0,1]
	s_waitcnt lgkmcnt(11)
	v_mul_f32_e32 v44, v36, v160
	v_mul_f32_e32 v60, v152, v36
	v_fmac_f32_e32 v44, v37, v161
	v_fmac_f32_e32 v60, v37, v153
	v_fmac_f32_e32 v44, v38, v162
	v_fmac_f32_e32 v60, v38, v154
	v_fmac_f32_e32 v44, v39, v163
	v_fmac_f32_e32 v60, v39, v155
	s_waitcnt lgkmcnt(6)
	v_pk_mul_f32 v[40:41], v[172:173], v[158:159] op_sel_hi:[1,0]
	v_pk_mul_f32 v[42:43], v[174:175], v[158:159] op_sel_hi:[1,0]
	v_add_f32_dpp v2, v44, v44 quad_perm:[1,0,3,2] row_mask:0xf bank_mask:0xf bound_ctrl:1
	v_pk_fma_f32 v[40:41], v[36:37], v[168:169], v[40:41]
	v_pk_fma_f32 v[42:43], v[38:39], v[170:171], v[42:43]
	v_add_f32_dpp v2, v2, v2 quad_perm:[2,3,0,1] row_mask:0xf bank_mask:0xf bound_ctrl:1
	ds_read_b128 v[136:139], v124 offset:29568
	ds_read_b128 v[140:143], v124 offset:29824
	ds_read_b128 v[144:147], v124 offset:30080
	ds_read_b128 v[148:151], v124 offset:30336
	ds_read_b128 v[152:155], v124 offset:30592
	ds_read_b32 v156, v110 offset:30848
	s_nop 1
	v_add_f32_dpp v2, v2, v2 row_ror:4 row_mask:0xf bank_mask:0xf bound_ctrl:1
	s_nop 1
	v_add_f32_dpp v2, v2, v2 row_ror:8 row_mask:0xf bank_mask:0xf bound_ctrl:1
	v_pk_fma_f32 v[36:37], v[164:165], v[2:3], v[40:41] op_sel_hi:[1,0,1]
	v_pk_fma_f32 v[38:39], v[166:167], v[2:3], v[42:43] op_sel_hi:[1,0,1]
	s_waitcnt lgkmcnt(11)
; #define LAS __attribute__((address_space(3)))
; __device__ __forceinline__ float row16_sum(float x) { x += dpp_mov<0xB1>(x); x += dpp_mov<0x4E>(x); x += dpp_mov<0x124>(x); x += dpp_mov<0x128>(x); return x; }
; __device__ __forceinline__ void scan_phase(const KAS Args& a, LAS unsigned char* lds, int i, const int tid_, const int bid, const int nblk) {
;     ...
;                 for (int t = 0; t < TC; ++t) {
;                     f32x4 kk4n = kk4, nb4n = nb4, w4n = w4, k4n = k4, r4n = r4; float vn = v;
;                     if (t + 1 < TC) { const LAS float* sn = sb + (t + 1) * SST;
;                         kk4n = *(const LAS f32x4*)(sn); nb4n = *(const LAS f32x4*)(sn + 64); w4n = *(const LAS f32x4*)(sn + 128); k4n = *(const LAS f32x4*)(sn + 192); r4n = *(const LAS f32x4*)(sn + 256); vn = vb[(t + 1) * SST]; }
;                     __builtin_amdgcn_sched_barrier(0x6);
;                     float sa = fmaf(S[3], kk4[3], fmaf(S[2], kk4[2], fmaf(S[1], kk4[1], S[0] * kk4[0])));
;                     const f32x4 Tm = S * w4 + k4 * v;
;                     sa = row16_sum(sa);
;                     S = Tm + nb4 * sa;
;                     float y = fmaf(S[3], r4[3], fmaf(S[2], r4[2], fmaf(S[1], r4[1], S[0] * r4[0]))); y = row16_sum(y);
;                     ysel = (cgp == (t & 15)) ? y : ysel;
;                     if ((t & 15) == 15) yb[(t - 15 + cgp) * 32 + rl] = ysel;
;                     kk4 = kk4n; nb4 = nb4n; w4 = w4n; k4 = k4n; r4 = r4n; v = vn; }
	v_mul_f32_e32 v44, v36, v188
	v_mul_f32_e32 v62, v176, v36
	v_fmac_f32_e32 v44, v37, v189
	v_fmac_f32_e32 v62, v37, v177
	v_fmac_f32_e32 v44, v38, v190
	v_fmac_f32_e32 v62, v38, v178
	v_fmac_f32_e32 v44, v39, v191
	v_fmac_f32_e32 v62, v39, v179
	s_waitcnt lgkmcnt(6)
	v_pk_mul_f32 v[40:41], v[200:201], v[208:209] op_sel_hi:[1,0]
	v_pk_mul_f32 v[42:43], v[202:203], v[208:209] op_sel_hi:[1,0]
	v_add_f32_dpp v2, v44, v44 quad_perm:[1,0,3,2] row_mask:0xf bank_mask:0xf bound_ctrl:1
	v_pk_fma_f32 v[40:41], v[36:37], v[196:197], v[40:41]
	v_pk_fma_f32 v[42:43], v[38:39], v[198:199], v[42:43]
	v_add_f32_dpp v2, v2, v2 quad_perm:[2,3,0,1] row_mask:0xf bank_mask:0xf bound_ctrl:1
	v_cndmask_b32_e64 v56, v60, v62, s[8:9]
	v_cndmask_b32_e64 v57, v62, v60, s[8:9]
	s_nop 1
	v_add_f32_dpp v63, v57, v56 quad_perm:[1,0,3,2] row_mask:0xf bank_mask:0xf bound_ctrl:1
	v_cndmask_b32_e64 v56, v51, v63, s[10:11]
	v_cndmask_b32_e64 v57, v63, v51, s[10:11]
	s_nop 1
	v_add_f32_dpp v65, v57, v56 quad_perm:[2,3,0,1] row_mask:0xf bank_mask:0xf bound_ctrl:1
	ds_read_b128 v[160:163], v124 offset:30976
	ds_read_b128 v[164:167], v124 offset:31232
	ds_read_b128 v[168:171], v124 offset:31488
	ds_read_b128 v[172:175], v124 offset:31744
	ds_read_b128 v[176:179], v124 offset:32000
	ds_read_b32 v158, v110 offset:32256
	v_add_f32_dpp v2, v2, v2 row_ror:4 row_mask:0xf bank_mask:0xf bound_ctrl:1
	s_nop 1
	v_add_f32_dpp v2, v2, v2 row_ror:8 row_mask:0xf bank_mask:0xf bound_ctrl:1
	v_pk_fma_f32 v[36:37], v[192:193], v[2:3], v[40:41] op_sel_hi:[1,0,1]
	v_pk_fma_f32 v[38:39], v[194:195], v[2:3], v[42:43] op_sel_hi:[1,0,1]
	s_waitcnt lgkmcnt(11)
	v_mul_f32_e32 v44, v36, v136
	v_mul_f32_e32 v66, v204, v36
	v_fmac_f32_e32 v44, v37, v137
	v_fmac_f32_e32 v66, v37, v205
	v_fmac_f32_e32 v44, v38, v138
	v_fmac_f32_e32 v66, v38, v206
	v_fmac_f32_e32 v44, v39, v139
	v_fmac_f32_e32 v66, v39, v207
	s_waitcnt lgkmcnt(6)
	v_pk_mul_f32 v[40:41], v[148:149], v[156:157] op_sel_hi:[1,0]
	v_pk_mul_f32 v[42:43], v[150:151], v[156:157] op_sel_hi:[1,0]
	v_add_f32_dpp v2, v44, v44 quad_perm:[1,0,3,2] row_mask:0xf bank_mask:0xf bound_ctrl:1
	v_pk_fma_f32 v[40:41], v[36:37], v[144:145], v[40:41]
	v_pk_fma_f32 v[42:43], v[38:39], v[146:147], v[42:43]
	v_add_f32_dpp v2, v2, v2 quad_perm:[2,3,0,1] row_mask:0xf bank_mask:0xf bound_ctrl:1
	ds_read_b128 v[188:191], v124 offset:32384
	ds_read_b128 v[192:195], v124 offset:32640
	ds_read_b128 v[196:199], v124 offset:32896
	ds_read_b128 v[200:203], v124 offset:33152
	ds_read_b128 v[204:207], v124 offset:33408
	ds_read_b32 v208, v110 offset:33664
	s_nop 1
	v_add_f32_dpp v2, v2, v2 row_ror:4 row_mask:0xf bank_mask:0xf bound_ctrl:1
	s_nop 1
	v_add_f32_dpp v2, v2, v2 row_ror:8 row_mask:0xf bank_mask:0xf bound_ctrl:1
	v_pk_fma_f32 v[36:37], v[140:141], v[2:3], v[40:41] op_sel_hi:[1,0,1]
	v_pk_fma_f32 v[38:39], v[142:143], v[2:3], v[42:43] op_sel_hi:[1,0,1]
	s_waitcnt lgkmcnt(11)
	v_mul_f32_e32 v44, v36, v160
	v_mul_f32_e32 v64, v152, v36
	v_fmac_f32_e32 v44, v37, v161
	v_fmac_f32_e32 v64, v37, v153
	v_fmac_f32_e32 v44, v38, v162
	v_fmac_f32_e32 v64, v38, v154
	v_fmac_f32_e32 v44, v39, v163
	v_fmac_f32_e32 v64, v39, v155
	s_waitcnt lgkmcnt(6)
	v_pk_mul_f32 v[40:41], v[172:173], v[158:159] op_sel_hi:[1,0]
	v_pk_mul_f32 v[42:43], v[174:175], v[158:159] op_sel_hi:[1,0]
	v_add_f32_dpp v2, v44, v44 quad_perm:[1,0,3,2] row_mask:0xf bank_mask:0xf bound_ctrl:1
	v_pk_fma_f32 v[40:41], v[36:37], v[168:169], v[40:41]
	v_pk_fma_f32 v[42:43], v[38:39], v[170:171], v[42:43]
	v_add_f32_dpp v2, v2, v2 quad_perm:[2,3,0,1] row_mask:0xf bank_mask:0xf bound_ctrl:1
	v_cndmask_b32_e64 v56, v66, v64, s[8:9]
	v_cndmask_b32_e64 v57, v64, v66, s[8:9]
	s_nop 1
	v_add_f32_dpp v67, v57, v56 quad_perm:[1,0,3,2] row_mask:0xf bank_mask:0xf bound_ctrl:1
	ds_read_b128 v[136:139], v124 offset:33792
	ds_read_b128 v[140:143], v124 offset:34048
	ds_read_b128 v[144:147], v124 offset:34304
	ds_read_b128 v[148:151], v124 offset:34560
	ds_read_b128 v[152:155], v124 offset:34816
	ds_read_b32 v156, v110 offset:35072
	v_add_f32_dpp v2, v2, v2 row_ror:4 row_mask:0xf bank_mask:0xf bound_ctrl:1
	s_nop 1
	v_add_f32_dpp v2, v2, v2 row_ror:8 row_mask:0xf bank_mask:0xf bound_ctrl:1
	v_pk_fma_f32 v[36:37], v[164:165], v[2:3], v[40:41] op_sel_hi:[1,0,1]
	v_pk_fma_f32 v[38:39], v[166:167], v[2:3], v[42:43] op_sel_hi:[1,0,1]
	s_waitcnt lgkmcnt(11)
	v_mul_f32_e32 v44, v36, v188
	v_mul_f32_e32 v46, v176, v36
	v_fmac_f32_e32 v44, v37, v189
	v_fmac_f32_e32 v46, v37, v177
	v_fmac_f32_e32 v44, v38, v190
	v_fmac_f32_e32 v46, v38, v178
	v_fmac_f32_e32 v44, v39, v191
	v_fmac_f32_e32 v46, v39, v179
	s_waitcnt lgkmcnt(6)
	v_pk_mul_f32 v[40:41], v[200:201], v[208:209] op_sel_hi:[1,0]
	v_pk_mul_f32 v[42:43], v[202:203], v[208:209] op_sel_hi:[1,0]
	v_add_f32_dpp v2, v44, v44 quad_perm:[1,0,3,2] row_mask:0xf bank_mask:0xf bound_ctrl:1
	v_pk_fma_f32 v[40:41], v[36:37], v[196:197], v[40:41]
	v_pk_fma_f32 v[42:43], v[38:39], v[198:199], v[42:43]
	v_add_f32_dpp v2, v2, v2 quad_perm:[2,3,0,1] row_mask:0xf bank_mask:0xf bound_ctrl:1
	ds_read_b128 v[160:163], v124 offset:35200
	ds_read_b128 v[164:167], v124 offset:35456
	ds_read_b128 v[168:171], v124 offset:35712
	ds_read_b128 v[172:175], v124 offset:35968
	ds_read_b128 v[176:179], v124 offset:36224
	ds_read_b32 v158, v110 offset:36480
	s_nop 1
	v_add_f32_dpp v2, v2, v2 row_ror:4 row_mask:0xf bank_mask:0xf bound_ctrl:1
	s_nop 1
	v_add_f32_dpp v2, v2, v2 row_ror:8 row_mask:0xf bank_mask:0xf bound_ctrl:1
	v_pk_fma_f32 v[36:37], v[192:193], v[2:3], v[40:41] op_sel_hi:[1,0,1]
	v_pk_fma_f32 v[38:39], v[194:195], v[2:3], v[42:43] op_sel_hi:[1,0,1]
	s_waitcnt lgkmcnt(11)
; #define LAS __attribute__((address_space(3)))
; __device__ __forceinline__ float row16_sum(float x) { x += dpp_mov<0xB1>(x); x += dpp_mov<0x4E>(x); x += dpp_mov<0x124>(x); x += dpp_mov<0x128>(x); return x; }
; __device__ __forceinline__ void scan_phase(const KAS Args& a, LAS unsigned char* lds, int i, const int tid_, const int bid, const int nblk) {
;     ...
;                 for (int t = 0; t < TC; ++t) {
;                     f32x4 kk4n = kk4, nb4n = nb4, w4n = w4, k4n = k4, r4n = r4; float vn = v;
;                     if (t + 1 < TC) { const LAS float* sn = sb + (t + 1) * SST;
;                         kk4n = *(const LAS f32x4*)(sn); nb4n = *(const LAS f32x4*)(sn + 64); w4n = *(const LAS f32x4*)(sn + 128); k4n = *(const LAS f32x4*)(sn + 192); r4n = *(const LAS f32x4*)(sn + 256); vn = vb[(t + 1) * SST]; }
;                     __builtin_amdgcn_sched_barrier(0x6);
;                     float sa = fmaf(S[3], kk4[3], fmaf(S[2], kk4[2], fmaf(S[1], kk4[1], S[0] * kk4[0])));
;                     const f32x4 Tm = S * w4 + k4 * v;
;                     sa = row16_sum(sa);
;                     S = Tm + nb4 * sa;
;                     float y = fmaf(S[3], r4[3], fmaf(S[2], r4[2], fmaf(S[1], r4[1], S[0] * r4[0]))); y = row16_sum(y);
;                     ysel = (cgp == (t & 15)) ? y : ysel;
;                     if ((t & 15) == 15) yb[(t - 15 + cgp) * 32 + rl] = ysel;
;                     kk4 = kk4n; nb4 = nb4n; w4 = w4n; k4 = k4n; r4 = r4n; v = vn; }
	v_mul_f32_e32 v44, v36, v136
	v_mul_f32_e32 v48, v204, v36
	v_fmac_f32_e32 v44, v37, v137
	v_fmac_f32_e32 v48, v37, v205
	v_fmac_f32_e32 v44, v38, v138
	v_fmac_f32_e32 v48, v38, v206
	v_fmac_f32_e32 v44, v39, v139
	v_fmac_f32_e32 v48, v39, v207
	s_waitcnt lgkmcnt(6)
	v_pk_mul_f32 v[40:41], v[148:149], v[156:157] op_sel_hi:[1,0]
	v_pk_mul_f32 v[42:43], v[150:151], v[156:157] op_sel_hi:[1,0]
	v_add_f32_dpp v2, v44, v44 quad_perm:[1,0,3,2] row_mask:0xf bank_mask:0xf bound_ctrl:1
	v_pk_fma_f32 v[40:41], v[36:37], v[144:145], v[40:41]
	v_pk_fma_f32 v[42:43], v[38:39], v[146:147], v[42:43]
	v_add_f32_dpp v2, v2, v2 quad_perm:[2,3,0,1] row_mask:0xf bank_mask:0xf bound_ctrl:1
	v_cndmask_b32_e64 v56, v46, v48, s[8:9]
	v_cndmask_b32_e64 v57, v48, v46, s[8:9]
	s_nop 1
	v_add_f32_dpp v47, v57, v56 quad_perm:[1,0,3,2] row_mask:0xf bank_mask:0xf bound_ctrl:1
	v_cndmask_b32_e64 v56, v67, v47, s[10:11]
	v_cndmask_b32_e64 v57, v47, v67, s[10:11]
	s_nop 1
	v_add_f32_dpp v50, v57, v56 quad_perm:[2,3,0,1] row_mask:0xf bank_mask:0xf bound_ctrl:1
	v_cndmask_b32_e64 v56, v65, v50, s[12:13]
	v_cndmask_b32_e64 v57, v50, v65, s[12:13]
	s_nop 1
	v_add_f32_dpp v49, v57, v56 row_shl:4 row_mask:0xf bank_mask:0x5
	s_nop 1
	v_add_f32_dpp v49, v57, v56 row_shr:4 row_mask:0xf bank_mask:0xa
	ds_read_b128 v[188:191], v124 offset:36608
	ds_read_b128 v[192:195], v124 offset:36864
	ds_read_b128 v[196:199], v124 offset:37120
	ds_read_b128 v[200:203], v124 offset:37376
	ds_read_b128 v[204:207], v124 offset:37632
	ds_read_b32 v208, v110 offset:37888
	v_add_f32_dpp v2, v2, v2 row_ror:4 row_mask:0xf bank_mask:0xf bound_ctrl:1
	s_nop 1
	v_add_f32_dpp v2, v2, v2 row_ror:8 row_mask:0xf bank_mask:0xf bound_ctrl:1
	v_pk_fma_f32 v[36:37], v[140:141], v[2:3], v[40:41] op_sel_hi:[1,0,1]
	v_pk_fma_f32 v[38:39], v[142:143], v[2:3], v[42:43] op_sel_hi:[1,0,1]
	s_waitcnt lgkmcnt(11)
	v_mul_f32_e32 v44, v36, v160
	v_mul_f32_e32 v52, v152, v36
	v_fmac_f32_e32 v44, v37, v161
	v_fmac_f32_e32 v52, v37, v153
	v_fmac_f32_e32 v44, v38, v162
	v_fmac_f32_e32 v52, v38, v154
	v_fmac_f32_e32 v44, v39, v163
	v_fmac_f32_e32 v52, v39, v155
	s_waitcnt lgkmcnt(6)
	v_pk_mul_f32 v[40:41], v[172:173], v[158:159] op_sel_hi:[1,0]
	v_pk_mul_f32 v[42:43], v[174:175], v[158:159] op_sel_hi:[1,0]
	v_add_f32_dpp v2, v44, v44 quad_perm:[1,0,3,2] row_mask:0xf bank_mask:0xf bound_ctrl:1
	v_pk_fma_f32 v[40:41], v[36:37], v[168:169], v[40:41]
	v_pk_fma_f32 v[42:43], v[38:39], v[170:171], v[42:43]
	v_add_f32_dpp v2, v2, v2 quad_perm:[2,3,0,1] row_mask:0xf bank_mask:0xf bound_ctrl:1
	ds_read_b128 v[136:139], v124 offset:38016
	ds_read_b128 v[140:143], v124 offset:38272
	ds_read_b128 v[144:147], v124 offset:38528
	ds_read_b128 v[148:151], v124 offset:38784
	ds_read_b128 v[152:155], v124 offset:39040
	ds_read_b32 v156, v110 offset:39296
	s_nop 1
	v_add_f32_dpp v2, v2, v2 row_ror:4 row_mask:0xf bank_mask:0xf bound_ctrl:1
	s_nop 1
	v_add_f32_dpp v2, v2, v2 row_ror:8 row_mask:0xf bank_mask:0xf bound_ctrl:1
	v_pk_fma_f32 v[36:37], v[164:165], v[2:3], v[40:41] op_sel_hi:[1,0,1]
	v_pk_fma_f32 v[38:39], v[166:167], v[2:3], v[42:43] op_sel_hi:[1,0,1]
	s_waitcnt lgkmcnt(11)
	v_mul_f32_e32 v44, v36, v188
	v_mul_f32_e32 v45, v176, v36
	v_fmac_f32_e32 v44, v37, v189
	v_fmac_f32_e32 v45, v37, v177
	v_fmac_f32_e32 v44, v38, v190
	v_fmac_f32_e32 v45, v38, v178
	v_fmac_f32_e32 v44, v39, v191
	v_fmac_f32_e32 v45, v39, v179
	s_waitcnt lgkmcnt(6)
	v_pk_mul_f32 v[40:41], v[200:201], v[208:209] op_sel_hi:[1,0]
	v_pk_mul_f32 v[42:43], v[202:203], v[208:209] op_sel_hi:[1,0]
	v_add_f32_dpp v2, v44, v44 quad_perm:[1,0,3,2] row_mask:0xf bank_mask:0xf bound_ctrl:1
	v_pk_fma_f32 v[40:41], v[36:37], v[196:197], v[40:41]
	v_pk_fma_f32 v[42:43], v[38:39], v[198:199], v[42:43]
	v_add_f32_dpp v2, v2, v2 quad_perm:[2,3,0,1] row_mask:0xf bank_mask:0xf bound_ctrl:1
	v_cndmask_b32_e64 v56, v52, v45, s[8:9]
	v_cndmask_b32_e64 v57, v45, v52, s[8:9]
	s_nop 1
	v_add_f32_dpp v53, v57, v56 quad_perm:[1,0,3,2] row_mask:0xf bank_mask:0xf bound_ctrl:1
	ds_read_b128 v[160:163], v124 offset:39424
	ds_read_b128 v[164:167], v124 offset:39680
	ds_read_b128 v[168:171], v124 offset:39936
	ds_read_b128 v[172:175], v124 offset:40192
	ds_read_b128 v[176:179], v124 offset:40448
	ds_read_b32 v158, v110 offset:40704
	v_add_f32_dpp v2, v2, v2 row_ror:4 row_mask:0xf bank_mask:0xf bound_ctrl:1
	s_nop 1
	v_add_f32_dpp v2, v2, v2 row_ror:8 row_mask:0xf bank_mask:0xf bound_ctrl:1
	v_pk_fma_f32 v[36:37], v[192:193], v[2:3], v[40:41] op_sel_hi:[1,0,1]
	v_pk_fma_f32 v[38:39], v[194:195], v[2:3], v[42:43] op_sel_hi:[1,0,1]
	s_waitcnt lgkmcnt(11)
	v_mul_f32_e32 v44, v36, v136
	v_mul_f32_e32 v61, v204, v36
	v_fmac_f32_e32 v44, v37, v137
	v_fmac_f32_e32 v61, v37, v205
	v_fmac_f32_e32 v44, v38, v138
	v_fmac_f32_e32 v61, v38, v206
	v_fmac_f32_e32 v44, v39, v139
	v_fmac_f32_e32 v61, v39, v207
	s_waitcnt lgkmcnt(6)
	v_pk_mul_f32 v[40:41], v[148:149], v[156:157] op_sel_hi:[1,0]
	v_pk_mul_f32 v[42:43], v[150:151], v[156:157] op_sel_hi:[1,0]
	v_add_f32_dpp v2, v44, v44 quad_perm:[1,0,3,2] row_mask:0xf bank_mask:0xf bound_ctrl:1
	v_pk_fma_f32 v[40:41], v[36:37], v[144:145], v[40:41]
	v_pk_fma_f32 v[42:43], v[38:39], v[146:147], v[42:43]
	v_add_f32_dpp v2, v2, v2 quad_perm:[2,3,0,1] row_mask:0xf bank_mask:0xf bound_ctrl:1
	ds_read_b128 v[188:191], v124 offset:40832
	ds_read_b128 v[192:195], v124 offset:41088
	ds_read_b128 v[196:199], v124 offset:41344
	ds_read_b128 v[200:203], v124 offset:41600
	ds_read_b128 v[204:207], v124 offset:41856
	ds_read_b32 v208, v110 offset:42112
	s_nop 1
	v_add_f32_dpp v2, v2, v2 row_ror:4 row_mask:0xf bank_mask:0xf bound_ctrl:1
	s_nop 1
	v_add_f32_dpp v2, v2, v2 row_ror:8 row_mask:0xf bank_mask:0xf bound_ctrl:1
	v_pk_fma_f32 v[36:37], v[140:141], v[2:3], v[40:41] op_sel_hi:[1,0,1]
	v_pk_fma_f32 v[38:39], v[142:143], v[2:3], v[42:43] op_sel_hi:[1,0,1]
	s_waitcnt lgkmcnt(11)
; #define LAS __attribute__((address_space(3)))
; __device__ __forceinline__ float row16_sum(float x) { x += dpp_mov<0xB1>(x); x += dpp_mov<0x4E>(x); x += dpp_mov<0x124>(x); x += dpp_mov<0x128>(x); return x; }
; __device__ __forceinline__ void scan_phase(const KAS Args& a, LAS unsigned char* lds, int i, const int tid_, const int bid, const int nblk) {
;     ...
;                 for (int t = 0; t < TC; ++t) {
;                     f32x4 kk4n = kk4, nb4n = nb4, w4n = w4, k4n = k4, r4n = r4; float vn = v;
;                     if (t + 1 < TC) { const LAS float* sn = sb + (t + 1) * SST;
;                         kk4n = *(const LAS f32x4*)(sn); nb4n = *(const LAS f32x4*)(sn + 64); w4n = *(const LAS f32x4*)(sn + 128); k4n = *(const LAS f32x4*)(sn + 192); r4n = *(const LAS f32x4*)(sn + 256); vn = vb[(t + 1) * SST]; }
;                     __builtin_amdgcn_sched_barrier(0x6);
;                     float sa = fmaf(S[3], kk4[3], fmaf(S[2], kk4[2], fmaf(S[1], kk4[1], S[0] * kk4[0])));
;                     const f32x4 Tm = S * w4 + k4 * v;
;                     sa = row16_sum(sa);
;                     S = Tm + nb4 * sa;
;                     float y = fmaf(S[3], r4[3], fmaf(S[2], r4[2], fmaf(S[1], r4[1], S[0] * r4[0]))); y = row16_sum(y);
;                     ysel = (cgp == (t & 15)) ? y : ysel;
;                     if ((t & 15) == 15) yb[(t - 15 + cgp) * 32 + rl] = ysel;
;                     kk4 = kk4n; nb4 = nb4n; w4 = w4n; k4 = k4n; r4 = r4n; v = vn; }
	v_mul_f32_e32 v44, v36, v160
	v_mul_f32_e32 v55, v152, v36
	v_fmac_f32_e32 v44, v37, v161
	v_fmac_f32_e32 v55, v37, v153
	v_fmac_f32_e32 v44, v38, v162
	v_fmac_f32_e32 v55, v38, v154
	v_fmac_f32_e32 v44, v39, v163
	v_fmac_f32_e32 v55, v39, v155
	s_waitcnt lgkmcnt(6)
	v_pk_mul_f32 v[40:41], v[172:173], v[158:159] op_sel_hi:[1,0]
	v_pk_mul_f32 v[42:43], v[174:175], v[158:159] op_sel_hi:[1,0]
	v_add_f32_dpp v2, v44, v44 quad_perm:[1,0,3,2] row_mask:0xf bank_mask:0xf bound_ctrl:1
	v_pk_fma_f32 v[40:41], v[36:37], v[168:169], v[40:41]
	v_pk_fma_f32 v[42:43], v[38:39], v[170:171], v[42:43]
	v_add_f32_dpp v2, v2, v2 quad_perm:[2,3,0,1] row_mask:0xf bank_mask:0xf bound_ctrl:1
	v_cndmask_b32_e64 v56, v61, v55, s[8:9]
	v_cndmask_b32_e64 v57, v55, v61, s[8:9]
	s_nop 1
	v_add_f32_dpp v58, v57, v56 quad_perm:[1,0,3,2] row_mask:0xf bank_mask:0xf bound_ctrl:1
	v_cndmask_b32_e64 v56, v53, v58, s[10:11]
	v_cndmask_b32_e64 v57, v58, v53, s[10:11]
	s_nop 1
	v_add_f32_dpp v54, v57, v56 quad_perm:[2,3,0,1] row_mask:0xf bank_mask:0xf bound_ctrl:1
	ds_read_b128 v[136:139], v124 offset:42240
	ds_read_b128 v[140:143], v124 offset:42496
	ds_read_b128 v[144:147], v124 offset:42752
	ds_read_b128 v[148:151], v124 offset:43008
	ds_read_b128 v[152:155], v124 offset:43264
	ds_read_b32 v156, v110 offset:43520
	v_add_f32_dpp v2, v2, v2 row_ror:4 row_mask:0xf bank_mask:0xf bound_ctrl:1
	s_nop 1
	v_add_f32_dpp v2, v2, v2 row_ror:8 row_mask:0xf bank_mask:0xf bound_ctrl:1
	v_pk_fma_f32 v[36:37], v[164:165], v[2:3], v[40:41] op_sel_hi:[1,0,1]
	v_pk_fma_f32 v[38:39], v[166:167], v[2:3], v[42:43] op_sel_hi:[1,0,1]
	s_waitcnt lgkmcnt(11)
	v_mul_f32_e32 v44, v36, v188
	v_mul_f32_e32 v59, v176, v36
	v_fmac_f32_e32 v44, v37, v189
	v_fmac_f32_e32 v59, v37, v177
	v_fmac_f32_e32 v44, v38, v190
	v_fmac_f32_e32 v59, v38, v178
	v_fmac_f32_e32 v44, v39, v191
	v_fmac_f32_e32 v59, v39, v179
	s_waitcnt lgkmcnt(6)
	v_pk_mul_f32 v[40:41], v[200:201], v[208:209] op_sel_hi:[1,0]
	v_pk_mul_f32 v[42:43], v[202:203], v[208:209] op_sel_hi:[1,0]
	v_add_f32_dpp v2, v44, v44 quad_perm:[1,0,3,2] row_mask:0xf bank_mask:0xf bound_ctrl:1
	v_pk_fma_f32 v[40:41], v[36:37], v[196:197], v[40:41]
	v_pk_fma_f32 v[42:43], v[38:39], v[198:199], v[42:43]
	v_add_f32_dpp v2, v2, v2 quad_perm:[2,3,0,1] row_mask:0xf bank_mask:0xf bound_ctrl:1
	ds_read_b128 v[160:163], v124 offset:43648
	ds_read_b128 v[164:167], v124 offset:43904
	ds_read_b128 v[168:171], v124 offset:44160
	ds_read_b128 v[172:175], v124 offset:44416
	ds_read_b128 v[176:179], v124 offset:44672
	ds_read_b32 v158, v110 offset:44928
	s_nop 1
	v_add_f32_dpp v2, v2, v2 row_ror:4 row_mask:0xf bank_mask:0xf bound_ctrl:1
	s_nop 1
	v_add_f32_dpp v2, v2, v2 row_ror:8 row_mask:0xf bank_mask:0xf bound_ctrl:1
	v_pk_fma_f32 v[36:37], v[192:193], v[2:3], v[40:41] op_sel_hi:[1,0,1]
	v_pk_fma_f32 v[38:39], v[194:195], v[2:3], v[42:43] op_sel_hi:[1,0,1]
	s_waitcnt lgkmcnt(11)
	v_mul_f32_e32 v44, v36, v136
	v_mul_f32_e32 v60, v204, v36
	v_fmac_f32_e32 v44, v37, v137
	v_fmac_f32_e32 v60, v37, v205
	v_fmac_f32_e32 v44, v38, v138
	v_fmac_f32_e32 v60, v38, v206
	v_fmac_f32_e32 v44, v39, v139
	v_fmac_f32_e32 v60, v39, v207
	s_waitcnt lgkmcnt(6)
	v_pk_mul_f32 v[40:41], v[148:149], v[156:157] op_sel_hi:[1,0]
	v_pk_mul_f32 v[42:43], v[150:151], v[156:157] op_sel_hi:[1,0]
	v_add_f32_dpp v2, v44, v44 quad_perm:[1,0,3,2] row_mask:0xf bank_mask:0xf bound_ctrl:1
	v_pk_fma_f32 v[40:41], v[36:37], v[144:145], v[40:41]
	v_pk_fma_f32 v[42:43], v[38:39], v[146:147], v[42:43]
	v_add_f32_dpp v2, v2, v2 quad_perm:[2,3,0,1] row_mask:0xf bank_mask:0xf bound_ctrl:1
	v_cndmask_b32_e64 v56, v59, v60, s[8:9]
	v_cndmask_b32_e64 v57, v60, v59, s[8:9]
	s_nop 1
	v_add_f32_dpp v62, v57, v56 quad_perm:[1,0,3,2] row_mask:0xf bank_mask:0xf bound_ctrl:1
	v_add_f32_dpp v2, v2, v2 row_ror:4 row_mask:0xf bank_mask:0xf bound_ctrl:1
	s_nop 1
	v_add_f32_dpp v2, v2, v2 row_ror:8 row_mask:0xf bank_mask:0xf bound_ctrl:1
	v_pk_fma_f32 v[36:37], v[140:141], v[2:3], v[40:41] op_sel_hi:[1,0,1]
	v_pk_fma_f32 v[38:39], v[142:143], v[2:3], v[42:43] op_sel_hi:[1,0,1]
	s_waitcnt lgkmcnt(5)
	v_mul_f32_e32 v44, v36, v160
	v_mul_f32_e32 v51, v152, v36
	v_fmac_f32_e32 v44, v37, v161
	v_fmac_f32_e32 v51, v37, v153
	v_fmac_f32_e32 v44, v38, v162
	v_fmac_f32_e32 v51, v38, v154
	v_fmac_f32_e32 v44, v39, v163
	v_fmac_f32_e32 v51, v39, v155
	s_waitcnt lgkmcnt(0)
	v_pk_mul_f32 v[40:41], v[172:173], v[158:159] op_sel_hi:[1,0]
	v_pk_mul_f32 v[42:43], v[174:175], v[158:159] op_sel_hi:[1,0]
	v_add_f32_dpp v2, v44, v44 quad_perm:[1,0,3,2] row_mask:0xf bank_mask:0xf bound_ctrl:1
	v_pk_fma_f32 v[40:41], v[36:37], v[168:169], v[40:41]
	v_pk_fma_f32 v[42:43], v[38:39], v[170:171], v[42:43]
	v_add_f32_dpp v2, v2, v2 quad_perm:[2,3,0,1] row_mask:0xf bank_mask:0xf bound_ctrl:1
	s_nop 1
	v_add_f32_dpp v2, v2, v2 row_ror:4 row_mask:0xf bank_mask:0xf bound_ctrl:1
	s_nop 1
	v_add_f32_dpp v2, v2, v2 row_ror:8 row_mask:0xf bank_mask:0xf bound_ctrl:1
	v_pk_fma_f32 v[36:37], v[164:165], v[2:3], v[40:41] op_sel_hi:[1,0,1]
	v_pk_fma_f32 v[38:39], v[166:167], v[2:3], v[42:43] op_sel_hi:[1,0,1]
	v_mul_f32_e32 v63, v176, v36
	v_fmac_f32_e32 v63, v37, v177
	v_fmac_f32_e32 v63, v38, v178
	v_fmac_f32_e32 v63, v39, v179
	v_cndmask_b32_e64 v56, v51, v63, s[8:9]
	v_cndmask_b32_e64 v57, v63, v51, s[8:9]
	s_nop 1
	v_add_f32_dpp v66, v57, v56 quad_perm:[1,0,3,2] row_mask:0xf bank_mask:0xf bound_ctrl:1
	v_cndmask_b32_e64 v56, v62, v66, s[10:11]
	v_cndmask_b32_e64 v57, v66, v62, s[10:11]
	s_nop 1
	v_add_f32_dpp v64, v57, v56 quad_perm:[2,3,0,1] row_mask:0xf bank_mask:0xf bound_ctrl:1
	v_cndmask_b32_e64 v56, v54, v64, s[12:13]
	v_cndmask_b32_e64 v57, v64, v54, s[12:13]
	s_nop 1
	v_add_f32_dpp v46, v57, v56 row_shl:4 row_mask:0xf bank_mask:0x5
	s_nop 1
	v_add_f32_dpp v46, v57, v56 row_shr:4 row_mask:0xf bank_mask:0xa
	v_cndmask_b32_e64 v56, v49, v46, s[14:15]
	v_cndmask_b32_e64 v57, v46, v49, s[14:15]
	s_nop 1
	v_add_f32_dpp v48, v57, v56 row_ror:8 row_mask:0xf bank_mask:0xf bound_ctrl:1
	ds_write_b32 v122, v48 offset:2048
	s_cbranch_vccnz .LBB0_183
; __device__ __forceinline__ float row16_sum(float x) { x += dpp_mov<0xB1>(x); x += dpp_mov<0x4E>(x); x += dpp_mov<0x124>(x); x += dpp_mov<0x128>(x); return x; }
; __device__ __forceinline__ void up4(const u32x2 w, float (&f)[4]) { f[0] = bflo(w.x); f[1] = bfhi(w.x); f[2] = bflo(w.y); f[3] = bfhi(w.y); }
; __device__ __forceinline__ void scan_stage(const u32x2 (&pz)[8], LAS float* buf, float* RKB, size_t mrow0, int t0, int tid, int h, int half, ...
;     ...
;     up4(pz[0], zr); up4(pz[1], zk); up4(pz[2], zv); up4(pz[3], zrp); up4(pz[4], zkp); up4(pz[5], zvp); up4(pz[6], ew); up4(pz[7], ic);
;     f32x4 r, k2, v, kkv, w; float n2 = 0.f, rkb = 0.f;
; #pragma unroll
;     for (int e = 0; e < 4; ++e) { r[e] = zr[e] + (zrp[e] - zr[e]) * mu_r[e]; const float k = zk[e] + (zkp[e] - zk[e]) * mu_k[e]; v[e] = zv[e] + (zvp[e] - zv[e]) * mu_v[e];
;         kkv[e] = k * kkc[e]; n2 += kkv[e] * kkv[e]; k2[e] = k * (1.0f + (ic[e] - 1.0f) * kac[e]); w[e] = __builtin_amdgcn_exp2f(-1.4426950408889634f * ew[e]); rkb += r[e] * k2[e] * rkc[e]; }
;     n2 = row16_sum(n2); rkb = row16_sum(rkb);
;     const float inv = __builtin_amdgcn_rsqf(fmaxf(n2, 1e-24f));
;     const f32x4 kkn = kkv * inv; f32x4 nb;
; #pragma unroll
;     for (int e = 0; e < 4; ++e) nb[e] = -kkn[e] * ic[e];
;     if (half == 0 && cgp == 0) RKB[(mrow0 + t0 + tl) * 8 + h] = rkb;
	s_waitcnt vmcnt(4)
	v_lshlrev_b32_e32 v28, 16, v80
	v_and_b32_e32 v29, 0xffff0000, v80
	v_lshlrev_b32_e32 v30, 16, v86
	v_and_b32_e32 v31, 0xffff0000, v86
	v_pk_add_f32 v[30:31], v[30:31], v[28:29] neg_lo:[0,1] neg_hi:[0,1]
	s_waitcnt vmcnt(3)
	v_lshlrev_b32_e32 v32, 16, v88
	v_pk_fma_f32 v[28:29], v[16:17], v[30:31], v[28:29]
	v_lshlrev_b32_e32 v30, 16, v82
	v_and_b32_e32 v31, 0xffff0000, v82
	v_and_b32_e32 v33, 0xffff0000, v88
	s_waitcnt vmcnt(0)
	v_lshlrev_b32_e32 v40, 16, v94
	v_and_b32_e32 v41, 0xffff0000, v94
	v_pk_add_f32 v[32:33], v[32:33], v[30:31] neg_lo:[0,1] neg_hi:[0,1]
	v_lshlrev_b32_e32 v46, 16, v89
	v_pk_fma_f32 v[30:31], v[20:21], v[32:33], v[30:31]
	v_pk_add_f32 v[32:33], v[40:41], -1.0 op_sel_hi:[1,0]
	v_pk_mul_f32 v[42:43], v[12:13], v[30:31]
	v_pk_fma_f32 v[32:33], v[24:25], v[32:33], 1.0 op_sel_hi:[1,1,0]
	v_and_b32_e32 v47, 0xffff0000, v89
	v_pk_mul_f32 v[32:33], v[30:31], v[32:33]
	v_lshlrev_b32_e32 v30, 16, v81
	v_pk_mul_f32 v[34:35], v[28:29], v[32:33]
	v_and_b32_e32 v31, 0xffff0000, v81
	v_fma_f32 v54, v4, v34, 0
	v_fmac_f32_e32 v54, v5, v35
	v_lshlrev_b32_e32 v34, 16, v87
	v_and_b32_e32 v35, 0xffff0000, v87
	v_pk_add_f32 v[34:35], v[34:35], v[30:31] neg_lo:[0,1] neg_hi:[0,1]
	v_lshlrev_b32_e32 v44, 16, v95
	v_pk_fma_f32 v[30:31], v[18:19], v[34:35], v[30:31]
	v_lshlrev_b32_e32 v34, 16, v83
	v_and_b32_e32 v35, 0xffff0000, v83
	v_and_b32_e32 v45, 0xffff0000, v95
	v_pk_add_f32 v[46:47], v[46:47], v[34:35] neg_lo:[0,1] neg_hi:[0,1]
	v_pk_mul_f32 v[48:49], v[42:43], v[42:43]
	v_pk_fma_f32 v[46:47], v[22:23], v[46:47], v[34:35]
	v_pk_add_f32 v[34:35], v[44:45], -1.0 op_sel_hi:[1,0]
	v_add_f32_e32 v2, v48, v49
	v_pk_fma_f32 v[34:35], v[26:27], v[34:35], 1.0 op_sel_hi:[1,1,0]
	v_mov_b32_e32 v48, 0
	v_pk_mul_f32 v[34:35], v[46:47], v[34:35]
	v_pk_mul_f32 v[46:47], v[14:15], v[46:47]
	v_pk_mul_f32 v[50:51], v[30:31], v[34:35]
	v_pk_mul_f32 v[52:53], v[46:47], v[46:47]
	v_fmac_f32_e32 v54, v6, v50
	v_add_f32_e32 v2, v52, v2
	v_add_f32_e32 v2, v53, v2
	v_fmac_f32_e32 v54, v7, v51
	v_mov_b32_e32 v50, 0
	v_add_f32_dpp v2, v2, v2 quad_perm:[1,0,3,2] row_mask:0xf bank_mask:0xf bound_ctrl:1
	v_add_f32_dpp v49, v54, v54 quad_perm:[1,0,3,2] row_mask:0xf bank_mask:0xf bound_ctrl:1
	s_nop 0
	v_add_f32_dpp v2, v2, v2 quad_perm:[2,3,0,1] row_mask:0xf bank_mask:0xf bound_ctrl:1
	v_add_f32_dpp v49, v49, v49 quad_perm:[2,3,0,1] row_mask:0xf bank_mask:0xf bound_ctrl:1
	s_nop 0
	v_add_f32_dpp v2, v2, v2 row_ror:4 row_mask:0xf bank_mask:0xf bound_ctrl:1
	v_add_f32_dpp v49, v49, v49 row_ror:4 row_mask:0xf bank_mask:0xf bound_ctrl:1
	s_nop 0
	v_mov_b32_dpp v48, v2 row_ror:8 row_mask:0xf bank_mask:0xf
	v_mov_b32_dpp v50, v49 row_ror:8 row_mask:0xf bank_mask:0xf
	s_and_saveexec_b64 s[2:3], s[42:43]
	s_cbranch_execz .LBB0_193
	v_lshl_add_u64 v[52:53], s[88:89], 0, v[100:101]
	v_add_f32_e32 v49, v49, v50
	global_store_dword v[52:53], v49, off
